# SO9: per-block output flush moved off the all-wave path: waves 4-7 store the previous block's OBUF in their idle part of the fourth segment (counted vmcnt keeps the stores in flight across the barrier
# speedup vs baseline: 1.0013x; 1.0013x over previous
.LBB0_382:
	s_andn2_b64 vcc, exec, s[10:11]
	s_cbranch_vccnz .LBB0_454
	s_and_b64 s[10:11], s[12:13], exec
	s_cselect_b32 s10, 4, 2
	s_lshr_b32 s5, s0, 7
	s_lshl_b32 s7, s5, 12
	s_lshl_b32 s3, s1, 3
	s_add_i32 s33, s74, -1
	s_add_i32 s75, s7, 0
	s_bfe_u32 s11, s0, 0x10006
	s_bitcmp1_b32 s0, 6
	s_cselect_b64 s[88:89], -1, 0
	s_and_b32 s0, s0, 0x3fffff80
	s_lshl_b32 s0, s0, 2
	s_add_i32 s62, s0, 0
	s_lshl_b32 s0, s1, 12
	s_add_i32 s7, s0, 0
	s_lshl_b32 s0, s1, 10
	s_lshl_b32 s77, s5, 10
	s_add_i32 s0, s0, 0
	s_lshl_b32 s5, s1, 11
	s_add_i32 s44, s0, 0x1e800
	s_add_i32 s51, s0, 0x1a800
	s_add_i32 s5, s5, 0
	s_add_i32 s18, s0, 0x1b800
	s_add_i32 s12, s1, -4
	s_lshl_b32 s0, s30, 16
	s_lshl_b32 s13, s56, 12
	s_add_i32 s76, s75, 0x14800
	s_add_i32 s62, s62, 0x1f800
	s_add_i32 s63, s74, 0xffffff80
	s_lshl_b32 s59, s56, 6
	s_add_i32 s5, s5, 0x1c800
	s_or_b32 s14, s13, s0
	s_lshl_b32 s13, s12, 1
	s_add_i32 s71, s74, -8
	s_lshl_b32 s0, s12, 4
	s_cmp_lt_u32 s1, s10
	s_cselect_b64 s[90:91], -1, 0
	s_lshl_b32 s12, s12, 11
	v_readlane_b32 s16, v255, 29
	s_add_i32 s34, s12, 0
	s_or_b32 s12, s13, 1
	v_readlane_b32 s17, v255, 30
	s_lshl_b32 s60, s12, 3
	s_lshl_b32 s12, s12, 10
	s_lshl_b32 s10, s11, 10
	s_lshl_b32 s35, s1, 5
	s_lshl_b32 s15, s30, 11
	s_lshl_b32 s11, s11, 5
	s_nor_b64 s[92:93], s[82:83], s[16:17]
	s_add_i32 s61, s12, 0
	s_lshl_b32 s12, s56, 3
	v_readlane_b32 s13, v255, 23
	s_add_u32 s12, s13, s12
	v_readlane_b32 s13, v255, 24
	s_addc_u32 s13, s13, 0
	s_lshl_b32 s16, s30, 2
	s_add_u32 s94, s12, s16
	s_addc_u32 s95, s13, 0
	s_lshl_b32 s12, s30, 7
	s_add_u32 s96, s54, s12
	s_addc_u32 s97, s55, 0
	s_lshl_b32 s12, s56, 7
	s_add_u32 s54, s36, s12
	s_addc_u32 s55, s37, 0
	s_add_u32 s52, s52, s12
	s_addc_u32 s53, s53, 0
	s_add_u32 s12, s42, s12
	s_addc_u32 s13, s43, 0
	s_add_i32 s15, s81, s15
	s_add_i32 s15, s15, s31
	v_writelane_b32 v255, s56, 59
	s_mov_b32 s42, s18
	s_add_i32 s66, s48, s33
	s_add_i32 s67, s15, 0x800
	s_or_b32 s70, s10, 0x18800
	s_lshl_b32 s30, s14, 1
	s_lshl_b32 s72, s11, 1
	v_lshrrev_b32_e32 v34, 3, v1
	v_and_b32_e32 v35, 7, v1
	v_lshlrev_b32_e32 v35, 4, v35
	v_add_u32_e32 v34, s3, v34
	v_mov_b32_e32 v36, s12
	v_mov_b32_e32 v37, s13
	v_mov_b32_e32 v38, s52
	v_mov_b32_e32 v39, s53
	v_mov_b32_e32 v40, s54
	v_mov_b32_e32 v41, s55
	v_mov_b32_e32 v42, s96
	v_mov_b32_e32 v43, s97
	v_lshl_add_u64 v[44:45], v[42:43], 0, s[68:69]
	v_mov_b32_e32 v49, 0x800
	v_mov_b32_e32 v50, 0x200
	v_mov_b32_e32 v46, v34
	v_min_i32_e32 v46, 0x149, v46
	v_mul_hi_i32 v47, v46, s6
	v_ashrrev_i32_e32 v47, 1, v47
	v_mul_u32_u24_e32 v48, 5, v47
	v_sub_u32_e32 v48, v46, v48
	v_mov_b32_e32 v226, v47
	v_cmp_gt_u32_e32 vcc, 3, v48
	v_mov_b32_e32 v51, v36
	v_mov_b32_e32 v52, v37
	v_cndmask_b32_e32 v227, v50, v49, vcc
	v_cmp_eq_u32_e32 vcc, 1, v48
	s_nop 1
	v_cndmask_b32_e32 v51, v51, v38, vcc
	v_cndmask_b32_e32 v52, v52, v39, vcc
	v_cmp_eq_u32_e32 vcc, 2, v48
	s_nop 1
	v_cndmask_b32_e32 v51, v51, v40, vcc
	v_cndmask_b32_e32 v52, v52, v41, vcc
	v_cmp_eq_u32_e32 vcc, 3, v48
	s_nop 1
	v_cndmask_b32_e32 v51, v51, v42, vcc
	v_cndmask_b32_e32 v52, v52, v43, vcc
	v_cmp_eq_u32_e32 vcc, 4, v48
	s_nop 1
	v_cndmask_b32_e32 v51, v51, v44, vcc
	v_cndmask_b32_e32 v52, v52, v45, vcc
	v_mul_lo_u32 v53, s48, v227
	v_add_u32_e32 v53, v53, v35
	v_add_co_u32_e32 v228, vcc, v51, v53
	s_nop 1
	v_addc_co_u32_e32 v229, vcc, 0, v52, vcc
	v_add_u32_e32 v46, 64, v34
	v_min_i32_e32 v46, 0x149, v46
	v_mul_hi_i32 v47, v46, s6
	v_ashrrev_i32_e32 v47, 1, v47
	v_mul_u32_u24_e32 v48, 5, v47
	v_sub_u32_e32 v48, v46, v48
	v_mov_b32_e32 v230, v47
	v_cmp_gt_u32_e32 vcc, 3, v48
	v_mov_b32_e32 v51, v36
	v_mov_b32_e32 v52, v37
	v_cndmask_b32_e32 v231, v50, v49, vcc
	v_cmp_eq_u32_e32 vcc, 1, v48
	s_nop 1
	v_cndmask_b32_e32 v51, v51, v38, vcc
	v_cndmask_b32_e32 v52, v52, v39, vcc
	v_cmp_eq_u32_e32 vcc, 2, v48
	s_nop 1
	v_cndmask_b32_e32 v51, v51, v40, vcc
	v_cndmask_b32_e32 v52, v52, v41, vcc
	v_cmp_eq_u32_e32 vcc, 3, v48
	s_nop 1
	v_cndmask_b32_e32 v51, v51, v42, vcc
	v_cndmask_b32_e32 v52, v52, v43, vcc
	v_cmp_eq_u32_e32 vcc, 4, v48
	s_nop 1
	v_cndmask_b32_e32 v51, v51, v44, vcc
	v_cndmask_b32_e32 v52, v52, v45, vcc
	v_mul_lo_u32 v53, s48, v231
	v_add_u32_e32 v53, v53, v35
	v_add_co_u32_e32 v232, vcc, v51, v53
	s_nop 1
	v_addc_co_u32_e32 v233, vcc, 0, v52, vcc
	v_add_u32_e32 v46, 128, v34
	v_min_i32_e32 v46, 0x149, v46
	v_mul_hi_i32 v47, v46, s6
	v_ashrrev_i32_e32 v47, 1, v47
	v_mul_u32_u24_e32 v48, 5, v47
	v_sub_u32_e32 v48, v46, v48
	v_mov_b32_e32 v234, v47
	v_cmp_gt_u32_e32 vcc, 3, v48
	v_mov_b32_e32 v51, v36
	v_mov_b32_e32 v52, v37
	v_cndmask_b32_e32 v235, v50, v49, vcc
	v_cmp_eq_u32_e32 vcc, 1, v48
	s_nop 1
	v_cndmask_b32_e32 v51, v51, v38, vcc
	v_cndmask_b32_e32 v52, v52, v39, vcc
	v_cmp_eq_u32_e32 vcc, 2, v48
	s_nop 1
	v_cndmask_b32_e32 v51, v51, v40, vcc
	v_cndmask_b32_e32 v52, v52, v41, vcc
	v_cmp_eq_u32_e32 vcc, 3, v48
	s_nop 1
	v_cndmask_b32_e32 v51, v51, v42, vcc
	v_cndmask_b32_e32 v52, v52, v43, vcc
	v_cmp_eq_u32_e32 vcc, 4, v48
	s_nop 1
	v_cndmask_b32_e32 v51, v51, v44, vcc
	v_cndmask_b32_e32 v52, v52, v45, vcc
	v_mul_lo_u32 v53, s48, v235
	v_add_u32_e32 v53, v53, v35
	v_add_co_u32_e32 v236, vcc, v51, v53
	s_nop 1
	v_addc_co_u32_e32 v237, vcc, 0, v52, vcc
	v_add_u32_e32 v46, 192, v34
	v_min_i32_e32 v46, 0x149, v46
	v_mul_hi_i32 v47, v46, s6
	v_ashrrev_i32_e32 v47, 1, v47
	v_mul_u32_u24_e32 v48, 5, v47
	v_sub_u32_e32 v48, v46, v48
	v_mov_b32_e32 v238, v47
	v_cmp_gt_u32_e32 vcc, 3, v48
	v_mov_b32_e32 v51, v36
	v_mov_b32_e32 v52, v37
	v_cndmask_b32_e32 v239, v50, v49, vcc
	v_cmp_eq_u32_e32 vcc, 1, v48
	s_nop 1
	v_cndmask_b32_e32 v51, v51, v38, vcc
	v_cndmask_b32_e32 v52, v52, v39, vcc
	v_cmp_eq_u32_e32 vcc, 2, v48
	s_nop 1
	v_cndmask_b32_e32 v51, v51, v40, vcc
	v_cndmask_b32_e32 v52, v52, v41, vcc
	v_cmp_eq_u32_e32 vcc, 3, v48
	s_nop 1
	v_cndmask_b32_e32 v51, v51, v42, vcc
	v_cndmask_b32_e32 v52, v52, v43, vcc
	v_cmp_eq_u32_e32 vcc, 4, v48
	s_nop 1
	v_cndmask_b32_e32 v51, v51, v44, vcc
	v_cndmask_b32_e32 v52, v52, v45, vcc
	v_mul_lo_u32 v53, s48, v239
	v_add_u32_e32 v53, v53, v35
	v_add_co_u32_e32 v240, vcc, v51, v53
	s_nop 1
	v_addc_co_u32_e32 v241, vcc, 0, v52, vcc
	v_add_u32_e32 v46, 256, v34
	v_min_i32_e32 v46, 0x149, v46
	v_mul_hi_i32 v47, v46, s6
	v_ashrrev_i32_e32 v47, 1, v47
	v_mul_u32_u24_e32 v48, 5, v47
	v_sub_u32_e32 v48, v46, v48
	v_mov_b32_e32 v242, v47
	v_cmp_gt_u32_e32 vcc, 3, v48
	v_mov_b32_e32 v51, v36
	v_mov_b32_e32 v52, v37
	v_cndmask_b32_e32 v243, v50, v49, vcc
	v_cmp_eq_u32_e32 vcc, 1, v48
	s_nop 1
	v_cndmask_b32_e32 v51, v51, v38, vcc
	v_cndmask_b32_e32 v52, v52, v39, vcc
	v_cmp_eq_u32_e32 vcc, 2, v48
	s_nop 1
	v_cndmask_b32_e32 v51, v51, v40, vcc
	v_cndmask_b32_e32 v52, v52, v41, vcc
	v_cmp_eq_u32_e32 vcc, 3, v48
	s_nop 1
	v_cndmask_b32_e32 v51, v51, v42, vcc
	v_cndmask_b32_e32 v52, v52, v43, vcc
	v_cmp_eq_u32_e32 vcc, 4, v48
	s_nop 1
	v_cndmask_b32_e32 v51, v51, v44, vcc
	v_cndmask_b32_e32 v52, v52, v45, vcc
	v_mul_lo_u32 v53, s48, v243
	v_add_u32_e32 v53, v53, v35
	v_add_co_u32_e32 v244, vcc, v51, v53
	s_nop 1
	v_addc_co_u32_e32 v245, vcc, 0, v52, vcc
	v_add_u32_e32 v46, 320, v34
	v_min_i32_e32 v46, 0x149, v46
	v_mul_hi_i32 v47, v46, s6
	v_ashrrev_i32_e32 v47, 1, v47
	v_mul_u32_u24_e32 v48, 5, v47
	v_sub_u32_e32 v48, v46, v48
	v_mov_b32_e32 v246, v47
	v_cmp_gt_u32_e32 vcc, 3, v48
	v_mov_b32_e32 v51, v36
	v_mov_b32_e32 v52, v37
	v_cndmask_b32_e32 v247, v50, v49, vcc
	v_cmp_eq_u32_e32 vcc, 1, v48
	s_nop 1
	v_cndmask_b32_e32 v51, v51, v38, vcc
	v_cndmask_b32_e32 v52, v52, v39, vcc
	v_cmp_eq_u32_e32 vcc, 2, v48
	s_nop 1
	v_cndmask_b32_e32 v51, v51, v40, vcc
	v_cndmask_b32_e32 v52, v52, v41, vcc
	v_cmp_eq_u32_e32 vcc, 3, v48
	s_nop 1
	v_cndmask_b32_e32 v51, v51, v42, vcc
	v_cndmask_b32_e32 v52, v52, v43, vcc
	v_cmp_eq_u32_e32 vcc, 4, v48
	s_nop 1
	v_cndmask_b32_e32 v51, v51, v44, vcc
	v_cndmask_b32_e32 v52, v52, v45, vcc
	v_mul_lo_u32 v53, s48, v247
	v_add_u32_e32 v53, v53, v35
	v_add_co_u32_e32 v248, vcc, v51, v53
	s_nop 1
	v_addc_co_u32_e32 v249, vcc, 0, v52, vcc
	v_readlane_b32 s10, v255, 25
	v_readlane_b32 s11, v255, 26
	v_lshlrev_b32_e32 v34, 7, v1
	v_lshrrev_b32_e32 v36, 1, v1
	v_and_b32_e32 v34, 0x780, v34
	v_and_b32_e32 v36, -8, v36
	v_mov_b32_e32 v35, 0
	v_lshl_add_u32 v34, v36, 1, v34
	s_lshr_b32 s12, s1, 2
	s_lshl_b32 s12, s12, 18
	s_and_b32 s13, s1, 3
	s_lshl_b32 s13, s13, 11
	s_add_i32 s12, s12, s13
	s_add_i32 s12, s12, s30
	s_mov_b32 s13, 0
	v_lshl_add_u64 v[36:37], s[10:11], 0, v[34:35]
	v_lshl_add_u64 v[36:37], v[36:37], 0, s[12:13]
	s_lshl_b32 s12, s1, 11
	s_add_i32 s12, s12, 0x24000
	s_mov_b32 s13, m0
	s_mov_b32 m0, s12
	s_nop 0
	global_load_lds_dwordx4 v[36:37], off
	s_add_i32 s12, s12, 0x3c0
	s_mov_b32 m0, s12
	s_nop 0
	global_load_lds_dwordx4 v[36:37], off offset:64
	s_mov_b32 m0, s13
	s_mov_b32 s12, s49
	s_branch .LBB0_385

.LBB0_435:
	s_or_b64 exec, exec, s[10:11]
	s_branch .LBB0_436
.Lso9_fl:
	s_add_i32 s14, s12, 1
	s_cmp_le_u32 s49, s14
	s_cbranch_scc1 .LBB0_436
	v_add_u32_e32 v38, 0xfffff000, v212
	ds_read_b128 v[34:37], v212
	ds_read_b128 v[40:43], v38
	s_sub_i32 s14, s73, 64
	v_add_u32_e32 v39, s14, v103
	s_andn2_b64 vcc, exec, s[78:79]
	s_cbranch_vccnz .Lso9_fwd
	v_sub_u32_e32 v38, s66, v39
	s_mov_b64 s[10:11], s[64:65]
	s_mov_b32 s14, 0x10000
	s_mov_b32 s15, 0
	s_branch .Lso9_st
.Lso9_fwd:
	v_readlane_b32 s14, v255, 47
	v_readlane_b32 s15, v255, 48
	s_nop 1
	s_and_b64 vcc, exec, s[14:15]
	s_cbranch_vccz .Lso9_p2
	v_readlane_b32 s10, v255, 56
	s_nop 1
	v_add_u32_e32 v38, s10, v39
	v_readlane_b32 s10, v255, 19
	v_readlane_b32 s11, v255, 20
	s_branch .Lso9_fw2
.Lso9_p2:
	v_readlane_b32 s10, v255, 21
	v_add_u32_e32 v38, s81, v39
	v_readlane_b32 s11, v255, 22
.Lso9_fw2:
	s_mov_b32 s14, 0xffff0000
	s_mov_b32 s15, -1
.Lso9_st:
	v_ashrrev_i32_e32 v39, 31, v38
	v_lshlrev_b64 v[38:39], 11, v[38:39]
	v_mov_b32_e32 v44, v124
	v_lshl_add_u64 v[38:39], s[10:11], 0, v[38:39]
	s_lshl_b32 s40, s59, 1
	v_mov_b32_e32 v45, 0
	v_lshl_add_u64 v[38:39], v[38:39], 0, s[40:41]
	v_lshl_add_u64 v[38:39], v[38:39], 0, v[44:45]
	v_lshl_add_u64 v[44:45], v[38:39], 0, s[14:15]
	s_waitcnt lgkmcnt(0)
	global_store_dwordx4 v[38:39], v[34:37], off
	global_store_dwordx4 v[44:45], v[40:43], off
	s_waitcnt vmcnt(2)
	s_branch .Lso9_join

.LBB0_446:
	s_waitcnt lgkmcnt(0)
	s_barrier
	s_cmp_ge_u32 s49, s2
	s_cbranch_scc1 .Lso9_last
	s_add_i32 s67, s67, 64
	s_branch .LBB0_385
.Lso9_last:
	ds_read_b128 v[34:37], v212
	v_add_u32_e32 v39, s73, v103
	s_andn2_b64 vcc, exec, s[78:79]
	s_mov_b64 s[10:11], -1
	s_cbranch_vccnz .LBB0_448
	v_sub_u32_e32 v38, s66, v39
	s_mov_b64 s[10:11], 0
